# ssm_tables Toeplitz kernel: each thread forms C*B once per state and accumulates its 4 lags from it (3 VALU and 0.9 LDS reads per term instead of 7 and 2); this block was 12 us on the P0 critical path
# speedup vs baseline: 1.0029x; 1.0029x over previous
; __device__ __forceinline__ void ssm_tables(const Params& p, int g, int part, LAS float* sm, int tid) {
;     ...
;     if (fa < 64 && fb > 32) {
;         for (int e = tid; e < 2048; e += 512) { const int l = e >> 8, pch = (e >> 4) & 15, q = e & 15; float s = 0.f;
;             for (int n = 0; n < 64; ++n) { const float cr = cre[pch * 64 + n], ci = cim[pch * 64 + n], ar = pwr[l * 64 + n], ai = pwi[l * 64 + n];
;                 const float zr = cr * ar - ci * ai, zi = cr * ai + ci * ar; s += zr * bbr[n * 16 + q] - zi * bbi[n * 16 + q]; }
;             kc[e] = s; }
;     }
;     __syncthreads();
.LBB0_233:
	s_or_b64 exec, exec, s[20:21]
	s_ashr_i32 s24, s86, 5
	s_add_i32 s20, s24, -2
	s_cmp_lt_u32 s20, 4
	s_cselect_b64 s[20:21], -1, 0
	s_and_b64 s[22:23], s[6:7], s[20:21]
	s_waitcnt lgkmcnt(0)
	s_barrier
	s_and_saveexec_b64 s[20:21], s[22:23]
	s_cbranch_execz .LBB0_238
	v_and_b32_e32 v16, 15, v34
	v_bfe_u32 v17, v34, 4, 4
	v_lshrrev_b32_e32 v18, 8, v34
	v_lshlrev_b32_e32 v80, 8, v17
	v_add_u32_e32 v80, 0x3400, v80
	v_lshlrev_b32_e32 v81, 8, v18
	v_lshlrev_b32_e32 v82, 2, v16
	v_add_u32_e32 v82, 0x1400, v82
	v_add_u32_e32 v83, 0x2400, v82
	v_subrev_u32_e32 v83, 0x1400, v83
	v_mov_b32_e32 v84, 0
	v_mov_b32_e32 v85, 0
	v_mov_b32_e32 v86, 0
	v_mov_b32_e32 v87, 0
	ds_read_b128 v[88:91], v80 offset:0
	ds_read_b128 v[92:95], v80 offset:4096
	ds_read2_b32 v[96:97], v82 offset1:16
	ds_read2_b32 v[98:99], v82 offset0:32 offset1:48
	ds_read2_b32 v[100:101], v83 offset1:16
	ds_read2_b32 v[102:103], v83 offset0:32 offset1:48
	ds_read_b128 v[130:133], v81 offset:0
	ds_read_b128 v[134:137], v81 offset:2304
	ds_read_b128 v[138:141], v81 offset:512
	ds_read_b128 v[142:145], v81 offset:2816
	s_waitcnt lgkmcnt(4)
	v_mul_f32_e32 v18, v92, v100
	v_mul_f32_e32 v9, v88, v100
	v_fma_f32 v104, v88, v96, -v18
	v_fmac_f32_e32 v9, v92, v96
	v_mul_f32_e32 v18, v93, v101
	v_mul_f32_e32 v14, v89, v101
	v_fma_f32 v105, v89, v97, -v18
	v_fmac_f32_e32 v14, v93, v97
	v_mul_f32_e32 v18, v94, v102
	v_mul_f32_e32 v16, v90, v102
	v_fma_f32 v106, v90, v98, -v18
	v_fmac_f32_e32 v16, v94, v98
	v_mul_f32_e32 v18, v95, v103
	v_mul_f32_e32 v17, v91, v103
	v_fma_f32 v107, v91, v99, -v18
	v_fmac_f32_e32 v17, v95, v99
	v_add_u32_e32 v82, 0x100, v82
	v_add_u32_e32 v83, 0x100, v83
	s_waitcnt lgkmcnt(0)
	v_fmac_f32_e32 v84, v104, v130
	v_fma_f32 v84, -v9, v134, v84
	v_fmac_f32_e32 v84, v105, v131
	v_fma_f32 v84, -v14, v135, v84
	v_fmac_f32_e32 v84, v106, v132
	v_fma_f32 v84, -v16, v136, v84
	v_fmac_f32_e32 v84, v107, v133
	v_fma_f32 v84, -v17, v137, v84
	v_fmac_f32_e32 v85, v104, v138
	v_fma_f32 v85, -v9, v142, v85
	v_fmac_f32_e32 v85, v105, v139
	v_fma_f32 v85, -v14, v143, v85
	v_fmac_f32_e32 v85, v106, v140
	v_fma_f32 v85, -v16, v144, v85
	v_fmac_f32_e32 v85, v107, v141
	v_fma_f32 v85, -v17, v145, v85
	ds_read_b128 v[130:133], v81 offset:1024
	ds_read_b128 v[134:137], v81 offset:3328
	ds_read_b128 v[138:141], v81 offset:1536
	ds_read_b128 v[142:145], v81 offset:3840
	s_waitcnt lgkmcnt(0)
	v_fmac_f32_e32 v86, v104, v130
	v_fma_f32 v86, -v9, v134, v86
	v_fmac_f32_e32 v86, v105, v131
	v_fma_f32 v86, -v14, v135, v86
	v_fmac_f32_e32 v86, v106, v132
	v_fma_f32 v86, -v16, v136, v86
	v_fmac_f32_e32 v86, v107, v133
	v_fma_f32 v86, -v17, v137, v86
	v_fmac_f32_e32 v87, v104, v138
	v_fma_f32 v87, -v9, v142, v87
	v_fmac_f32_e32 v87, v105, v139
	v_fma_f32 v87, -v14, v143, v87
	v_fmac_f32_e32 v87, v106, v140
	v_fma_f32 v87, -v16, v144, v87
	v_fmac_f32_e32 v87, v107, v141
	v_fma_f32 v87, -v17, v145, v87
	ds_read_b128 v[88:91], v80 offset:16
	ds_read_b128 v[92:95], v80 offset:4112
	ds_read2_b32 v[96:97], v82 offset1:16
	ds_read2_b32 v[98:99], v82 offset0:32 offset1:48
	ds_read2_b32 v[100:101], v83 offset1:16
	ds_read2_b32 v[102:103], v83 offset0:32 offset1:48
	ds_read_b128 v[130:133], v81 offset:16
	ds_read_b128 v[134:137], v81 offset:2320
	ds_read_b128 v[138:141], v81 offset:528
	ds_read_b128 v[142:145], v81 offset:2832
	s_waitcnt lgkmcnt(4)
	v_mul_f32_e32 v18, v92, v100
	v_mul_f32_e32 v9, v88, v100
	v_fma_f32 v104, v88, v96, -v18
	v_fmac_f32_e32 v9, v92, v96
	v_mul_f32_e32 v18, v93, v101
	v_mul_f32_e32 v14, v89, v101
	v_fma_f32 v105, v89, v97, -v18
	v_fmac_f32_e32 v14, v93, v97
	v_mul_f32_e32 v18, v94, v102
	v_mul_f32_e32 v16, v90, v102
	v_fma_f32 v106, v90, v98, -v18
	v_fmac_f32_e32 v16, v94, v98
	v_mul_f32_e32 v18, v95, v103
	v_mul_f32_e32 v17, v91, v103
	v_fma_f32 v107, v91, v99, -v18
	v_fmac_f32_e32 v17, v95, v99
	v_add_u32_e32 v82, 0x100, v82
	v_add_u32_e32 v83, 0x100, v83
	s_waitcnt lgkmcnt(0)
	v_fmac_f32_e32 v84, v104, v130
	v_fma_f32 v84, -v9, v134, v84
	v_fmac_f32_e32 v84, v105, v131
	v_fma_f32 v84, -v14, v135, v84
	v_fmac_f32_e32 v84, v106, v132
	v_fma_f32 v84, -v16, v136, v84
	v_fmac_f32_e32 v84, v107, v133
	v_fma_f32 v84, -v17, v137, v84
	v_fmac_f32_e32 v85, v104, v138
	v_fma_f32 v85, -v9, v142, v85
	v_fmac_f32_e32 v85, v105, v139
	v_fma_f32 v85, -v14, v143, v85
	v_fmac_f32_e32 v85, v106, v140
	v_fma_f32 v85, -v16, v144, v85
	v_fmac_f32_e32 v85, v107, v141
	v_fma_f32 v85, -v17, v145, v85
	ds_read_b128 v[130:133], v81 offset:1040
	ds_read_b128 v[134:137], v81 offset:3344
	ds_read_b128 v[138:141], v81 offset:1552
	ds_read_b128 v[142:145], v81 offset:3856
	s_waitcnt lgkmcnt(0)
	v_fmac_f32_e32 v86, v104, v130
	v_fma_f32 v86, -v9, v134, v86
	v_fmac_f32_e32 v86, v105, v131
	v_fma_f32 v86, -v14, v135, v86
	v_fmac_f32_e32 v86, v106, v132
	v_fma_f32 v86, -v16, v136, v86
	v_fmac_f32_e32 v86, v107, v133
	v_fma_f32 v86, -v17, v137, v86
	v_fmac_f32_e32 v87, v104, v138
	v_fma_f32 v87, -v9, v142, v87
	v_fmac_f32_e32 v87, v105, v139
	v_fma_f32 v87, -v14, v143, v87
	v_fmac_f32_e32 v87, v106, v140
	v_fma_f32 v87, -v16, v144, v87
	v_fmac_f32_e32 v87, v107, v141
	v_fma_f32 v87, -v17, v145, v87
	ds_read_b128 v[88:91], v80 offset:32
	ds_read_b128 v[92:95], v80 offset:4128
	ds_read2_b32 v[96:97], v82 offset1:16
	ds_read2_b32 v[98:99], v82 offset0:32 offset1:48
	ds_read2_b32 v[100:101], v83 offset1:16
	ds_read2_b32 v[102:103], v83 offset0:32 offset1:48
	ds_read_b128 v[130:133], v81 offset:32
	ds_read_b128 v[134:137], v81 offset:2336
	ds_read_b128 v[138:141], v81 offset:544
	ds_read_b128 v[142:145], v81 offset:2848
	s_waitcnt lgkmcnt(4)
; __device__ __forceinline__ void ssm_tables(const Params& p, int g, int part, LAS float* sm, int tid) {
;     ...
;     if (fa < 64 && fb > 32) {
;         for (int e = tid; e < 2048; e += 512) { const int l = e >> 8, pch = (e >> 4) & 15, q = e & 15; float s = 0.f;
;             for (int n = 0; n < 64; ++n) { const float cr = cre[pch * 64 + n], ci = cim[pch * 64 + n], ar = pwr[l * 64 + n], ai = pwi[l * 64 + n];
;                 const float zr = cr * ar - ci * ai, zi = cr * ai + ci * ar; s += zr * bbr[n * 16 + q] - zi * bbi[n * 16 + q]; }
;             kc[e] = s; }
;     }
	v_mul_f32_e32 v18, v92, v100
	v_mul_f32_e32 v9, v88, v100
	v_fma_f32 v104, v88, v96, -v18
	v_fmac_f32_e32 v9, v92, v96
	v_mul_f32_e32 v18, v93, v101
	v_mul_f32_e32 v14, v89, v101
	v_fma_f32 v105, v89, v97, -v18
	v_fmac_f32_e32 v14, v93, v97
	v_mul_f32_e32 v18, v94, v102
	v_mul_f32_e32 v16, v90, v102
	v_fma_f32 v106, v90, v98, -v18
	v_fmac_f32_e32 v16, v94, v98
	v_mul_f32_e32 v18, v95, v103
	v_mul_f32_e32 v17, v91, v103
	v_fma_f32 v107, v91, v99, -v18
	v_fmac_f32_e32 v17, v95, v99
	v_add_u32_e32 v82, 0x100, v82
	v_add_u32_e32 v83, 0x100, v83
	s_waitcnt lgkmcnt(0)
	v_fmac_f32_e32 v84, v104, v130
	v_fma_f32 v84, -v9, v134, v84
	v_fmac_f32_e32 v84, v105, v131
	v_fma_f32 v84, -v14, v135, v84
	v_fmac_f32_e32 v84, v106, v132
	v_fma_f32 v84, -v16, v136, v84
	v_fmac_f32_e32 v84, v107, v133
	v_fma_f32 v84, -v17, v137, v84
	v_fmac_f32_e32 v85, v104, v138
	v_fma_f32 v85, -v9, v142, v85
	v_fmac_f32_e32 v85, v105, v139
	v_fma_f32 v85, -v14, v143, v85
	v_fmac_f32_e32 v85, v106, v140
	v_fma_f32 v85, -v16, v144, v85
	v_fmac_f32_e32 v85, v107, v141
	v_fma_f32 v85, -v17, v145, v85
	ds_read_b128 v[130:133], v81 offset:1056
	ds_read_b128 v[134:137], v81 offset:3360
	ds_read_b128 v[138:141], v81 offset:1568
	ds_read_b128 v[142:145], v81 offset:3872
	s_waitcnt lgkmcnt(0)
	v_fmac_f32_e32 v86, v104, v130
	v_fma_f32 v86, -v9, v134, v86
	v_fmac_f32_e32 v86, v105, v131
	v_fma_f32 v86, -v14, v135, v86
	v_fmac_f32_e32 v86, v106, v132
	v_fma_f32 v86, -v16, v136, v86
	v_fmac_f32_e32 v86, v107, v133
	v_fma_f32 v86, -v17, v137, v86
	v_fmac_f32_e32 v87, v104, v138
	v_fma_f32 v87, -v9, v142, v87
	v_fmac_f32_e32 v87, v105, v139
	v_fma_f32 v87, -v14, v143, v87
	v_fmac_f32_e32 v87, v106, v140
	v_fma_f32 v87, -v16, v144, v87
	v_fmac_f32_e32 v87, v107, v141
	v_fma_f32 v87, -v17, v145, v87
	ds_read_b128 v[88:91], v80 offset:48
	ds_read_b128 v[92:95], v80 offset:4144
	ds_read2_b32 v[96:97], v82 offset1:16
	ds_read2_b32 v[98:99], v82 offset0:32 offset1:48
	ds_read2_b32 v[100:101], v83 offset1:16
	ds_read2_b32 v[102:103], v83 offset0:32 offset1:48
	ds_read_b128 v[130:133], v81 offset:48
	ds_read_b128 v[134:137], v81 offset:2352
	ds_read_b128 v[138:141], v81 offset:560
	ds_read_b128 v[142:145], v81 offset:2864
	s_waitcnt lgkmcnt(4)
	v_mul_f32_e32 v18, v92, v100
	v_mul_f32_e32 v9, v88, v100
	v_fma_f32 v104, v88, v96, -v18
	v_fmac_f32_e32 v9, v92, v96
	v_mul_f32_e32 v18, v93, v101
	v_mul_f32_e32 v14, v89, v101
	v_fma_f32 v105, v89, v97, -v18
	v_fmac_f32_e32 v14, v93, v97
	v_mul_f32_e32 v18, v94, v102
	v_mul_f32_e32 v16, v90, v102
	v_fma_f32 v106, v90, v98, -v18
	v_fmac_f32_e32 v16, v94, v98
	v_mul_f32_e32 v18, v95, v103
	v_mul_f32_e32 v17, v91, v103
	v_fma_f32 v107, v91, v99, -v18
	v_fmac_f32_e32 v17, v95, v99
	v_add_u32_e32 v82, 0x100, v82
	v_add_u32_e32 v83, 0x100, v83
	s_waitcnt lgkmcnt(0)
	v_fmac_f32_e32 v84, v104, v130
	v_fma_f32 v84, -v9, v134, v84
	v_fmac_f32_e32 v84, v105, v131
	v_fma_f32 v84, -v14, v135, v84
	v_fmac_f32_e32 v84, v106, v132
	v_fma_f32 v84, -v16, v136, v84
	v_fmac_f32_e32 v84, v107, v133
	v_fma_f32 v84, -v17, v137, v84
	v_fmac_f32_e32 v85, v104, v138
	v_fma_f32 v85, -v9, v142, v85
	v_fmac_f32_e32 v85, v105, v139
	v_fma_f32 v85, -v14, v143, v85
	v_fmac_f32_e32 v85, v106, v140
	v_fma_f32 v85, -v16, v144, v85
	v_fmac_f32_e32 v85, v107, v141
	v_fma_f32 v85, -v17, v145, v85
	ds_read_b128 v[130:133], v81 offset:1072
	ds_read_b128 v[134:137], v81 offset:3376
	ds_read_b128 v[138:141], v81 offset:1584
	ds_read_b128 v[142:145], v81 offset:3888
	s_waitcnt lgkmcnt(0)
	v_fmac_f32_e32 v86, v104, v130
	v_fma_f32 v86, -v9, v134, v86
	v_fmac_f32_e32 v86, v105, v131
	v_fma_f32 v86, -v14, v135, v86
	v_fmac_f32_e32 v86, v106, v132
	v_fma_f32 v86, -v16, v136, v86
	v_fmac_f32_e32 v86, v107, v133
	v_fma_f32 v86, -v17, v137, v86
	v_fmac_f32_e32 v87, v104, v138
	v_fma_f32 v87, -v9, v142, v87
	v_fmac_f32_e32 v87, v105, v139
	v_fma_f32 v87, -v14, v143, v87
	v_fmac_f32_e32 v87, v106, v140
	v_fma_f32 v87, -v16, v144, v87
	v_fmac_f32_e32 v87, v107, v141
	v_fma_f32 v87, -v17, v145, v87
	ds_read_b128 v[88:91], v80 offset:64
	ds_read_b128 v[92:95], v80 offset:4160
	ds_read2_b32 v[96:97], v82 offset1:16
	ds_read2_b32 v[98:99], v82 offset0:32 offset1:48
	ds_read2_b32 v[100:101], v83 offset1:16
	ds_read2_b32 v[102:103], v83 offset0:32 offset1:48
	ds_read_b128 v[130:133], v81 offset:64
	ds_read_b128 v[134:137], v81 offset:2368
	ds_read_b128 v[138:141], v81 offset:576
	ds_read_b128 v[142:145], v81 offset:2880
	s_waitcnt lgkmcnt(4)
	v_mul_f32_e32 v18, v92, v100
	v_mul_f32_e32 v9, v88, v100
	v_fma_f32 v104, v88, v96, -v18
	v_fmac_f32_e32 v9, v92, v96
	v_mul_f32_e32 v18, v93, v101
	v_mul_f32_e32 v14, v89, v101
	v_fma_f32 v105, v89, v97, -v18
	v_fmac_f32_e32 v14, v93, v97
	v_mul_f32_e32 v18, v94, v102
	v_mul_f32_e32 v16, v90, v102
	v_fma_f32 v106, v90, v98, -v18
	v_fmac_f32_e32 v16, v94, v98
	v_mul_f32_e32 v18, v95, v103
	v_mul_f32_e32 v17, v91, v103
	v_fma_f32 v107, v91, v99, -v18
	v_fmac_f32_e32 v17, v95, v99
	v_add_u32_e32 v82, 0x100, v82
	v_add_u32_e32 v83, 0x100, v83
	s_waitcnt lgkmcnt(0)
	v_fmac_f32_e32 v84, v104, v130
	v_fma_f32 v84, -v9, v134, v84
	v_fmac_f32_e32 v84, v105, v131
	v_fma_f32 v84, -v14, v135, v84
	v_fmac_f32_e32 v84, v106, v132
	v_fma_f32 v84, -v16, v136, v84
	v_fmac_f32_e32 v84, v107, v133
	v_fma_f32 v84, -v17, v137, v84
	v_fmac_f32_e32 v85, v104, v138
	v_fma_f32 v85, -v9, v142, v85
	v_fmac_f32_e32 v85, v105, v139
	v_fma_f32 v85, -v14, v143, v85
	v_fmac_f32_e32 v85, v106, v140
	v_fma_f32 v85, -v16, v144, v85
	v_fmac_f32_e32 v85, v107, v141
	v_fma_f32 v85, -v17, v145, v85
	ds_read_b128 v[130:133], v81 offset:1088
	ds_read_b128 v[134:137], v81 offset:3392
	ds_read_b128 v[138:141], v81 offset:1600
	ds_read_b128 v[142:145], v81 offset:3904
	s_waitcnt lgkmcnt(0)
; __device__ __forceinline__ void ssm_tables(const Params& p, int g, int part, LAS float* sm, int tid) {
;     ...
;     if (fa < 64 && fb > 32) {
;         for (int e = tid; e < 2048; e += 512) { const int l = e >> 8, pch = (e >> 4) & 15, q = e & 15; float s = 0.f;
;             for (int n = 0; n < 64; ++n) { const float cr = cre[pch * 64 + n], ci = cim[pch * 64 + n], ar = pwr[l * 64 + n], ai = pwi[l * 64 + n];
;                 const float zr = cr * ar - ci * ai, zi = cr * ai + ci * ar; s += zr * bbr[n * 16 + q] - zi * bbi[n * 16 + q]; }
;             kc[e] = s; }
;     }
	v_fmac_f32_e32 v86, v104, v130
	v_fma_f32 v86, -v9, v134, v86
	v_fmac_f32_e32 v86, v105, v131
	v_fma_f32 v86, -v14, v135, v86
	v_fmac_f32_e32 v86, v106, v132
	v_fma_f32 v86, -v16, v136, v86
	v_fmac_f32_e32 v86, v107, v133
	v_fma_f32 v86, -v17, v137, v86
	v_fmac_f32_e32 v87, v104, v138
	v_fma_f32 v87, -v9, v142, v87
	v_fmac_f32_e32 v87, v105, v139
	v_fma_f32 v87, -v14, v143, v87
	v_fmac_f32_e32 v87, v106, v140
	v_fma_f32 v87, -v16, v144, v87
	v_fmac_f32_e32 v87, v107, v141
	v_fma_f32 v87, -v17, v145, v87
	ds_read_b128 v[88:91], v80 offset:80
	ds_read_b128 v[92:95], v80 offset:4176
	ds_read2_b32 v[96:97], v82 offset1:16
	ds_read2_b32 v[98:99], v82 offset0:32 offset1:48
	ds_read2_b32 v[100:101], v83 offset1:16
	ds_read2_b32 v[102:103], v83 offset0:32 offset1:48
	ds_read_b128 v[130:133], v81 offset:80
	ds_read_b128 v[134:137], v81 offset:2384
	ds_read_b128 v[138:141], v81 offset:592
	ds_read_b128 v[142:145], v81 offset:2896
	s_waitcnt lgkmcnt(4)
	v_mul_f32_e32 v18, v92, v100
	v_mul_f32_e32 v9, v88, v100
	v_fma_f32 v104, v88, v96, -v18
	v_fmac_f32_e32 v9, v92, v96
	v_mul_f32_e32 v18, v93, v101
	v_mul_f32_e32 v14, v89, v101
	v_fma_f32 v105, v89, v97, -v18
	v_fmac_f32_e32 v14, v93, v97
	v_mul_f32_e32 v18, v94, v102
	v_mul_f32_e32 v16, v90, v102
	v_fma_f32 v106, v90, v98, -v18
	v_fmac_f32_e32 v16, v94, v98
	v_mul_f32_e32 v18, v95, v103
	v_mul_f32_e32 v17, v91, v103
	v_fma_f32 v107, v91, v99, -v18
	v_fmac_f32_e32 v17, v95, v99
	v_add_u32_e32 v82, 0x100, v82
	v_add_u32_e32 v83, 0x100, v83
	s_waitcnt lgkmcnt(0)
	v_fmac_f32_e32 v84, v104, v130
	v_fma_f32 v84, -v9, v134, v84
	v_fmac_f32_e32 v84, v105, v131
	v_fma_f32 v84, -v14, v135, v84
	v_fmac_f32_e32 v84, v106, v132
	v_fma_f32 v84, -v16, v136, v84
	v_fmac_f32_e32 v84, v107, v133
	v_fma_f32 v84, -v17, v137, v84
	v_fmac_f32_e32 v85, v104, v138
	v_fma_f32 v85, -v9, v142, v85
	v_fmac_f32_e32 v85, v105, v139
	v_fma_f32 v85, -v14, v143, v85
	v_fmac_f32_e32 v85, v106, v140
	v_fma_f32 v85, -v16, v144, v85
	v_fmac_f32_e32 v85, v107, v141
	v_fma_f32 v85, -v17, v145, v85
	ds_read_b128 v[130:133], v81 offset:1104
	ds_read_b128 v[134:137], v81 offset:3408
	ds_read_b128 v[138:141], v81 offset:1616
	ds_read_b128 v[142:145], v81 offset:3920
	s_waitcnt lgkmcnt(0)
	v_fmac_f32_e32 v86, v104, v130
	v_fma_f32 v86, -v9, v134, v86
	v_fmac_f32_e32 v86, v105, v131
	v_fma_f32 v86, -v14, v135, v86
	v_fmac_f32_e32 v86, v106, v132
	v_fma_f32 v86, -v16, v136, v86
	v_fmac_f32_e32 v86, v107, v133
	v_fma_f32 v86, -v17, v137, v86
	v_fmac_f32_e32 v87, v104, v138
	v_fma_f32 v87, -v9, v142, v87
	v_fmac_f32_e32 v87, v105, v139
	v_fma_f32 v87, -v14, v143, v87
	v_fmac_f32_e32 v87, v106, v140
	v_fma_f32 v87, -v16, v144, v87
	v_fmac_f32_e32 v87, v107, v141
	v_fma_f32 v87, -v17, v145, v87
	ds_read_b128 v[88:91], v80 offset:96
	ds_read_b128 v[92:95], v80 offset:4192
	ds_read2_b32 v[96:97], v82 offset1:16
	ds_read2_b32 v[98:99], v82 offset0:32 offset1:48
	ds_read2_b32 v[100:101], v83 offset1:16
	ds_read2_b32 v[102:103], v83 offset0:32 offset1:48
	ds_read_b128 v[130:133], v81 offset:96
	ds_read_b128 v[134:137], v81 offset:2400
	ds_read_b128 v[138:141], v81 offset:608
	ds_read_b128 v[142:145], v81 offset:2912
	s_waitcnt lgkmcnt(4)
	v_mul_f32_e32 v18, v92, v100
	v_mul_f32_e32 v9, v88, v100
	v_fma_f32 v104, v88, v96, -v18
	v_fmac_f32_e32 v9, v92, v96
	v_mul_f32_e32 v18, v93, v101
	v_mul_f32_e32 v14, v89, v101
	v_fma_f32 v105, v89, v97, -v18
	v_fmac_f32_e32 v14, v93, v97
	v_mul_f32_e32 v18, v94, v102
	v_mul_f32_e32 v16, v90, v102
	v_fma_f32 v106, v90, v98, -v18
	v_fmac_f32_e32 v16, v94, v98
	v_mul_f32_e32 v18, v95, v103
	v_mul_f32_e32 v17, v91, v103
	v_fma_f32 v107, v91, v99, -v18
	v_fmac_f32_e32 v17, v95, v99
	v_add_u32_e32 v82, 0x100, v82
	v_add_u32_e32 v83, 0x100, v83
	s_waitcnt lgkmcnt(0)
	v_fmac_f32_e32 v84, v104, v130
	v_fma_f32 v84, -v9, v134, v84
	v_fmac_f32_e32 v84, v105, v131
	v_fma_f32 v84, -v14, v135, v84
	v_fmac_f32_e32 v84, v106, v132
	v_fma_f32 v84, -v16, v136, v84
	v_fmac_f32_e32 v84, v107, v133
	v_fma_f32 v84, -v17, v137, v84
	v_fmac_f32_e32 v85, v104, v138
	v_fma_f32 v85, -v9, v142, v85
	v_fmac_f32_e32 v85, v105, v139
	v_fma_f32 v85, -v14, v143, v85
	v_fmac_f32_e32 v85, v106, v140
	v_fma_f32 v85, -v16, v144, v85
	v_fmac_f32_e32 v85, v107, v141
	v_fma_f32 v85, -v17, v145, v85
	ds_read_b128 v[130:133], v81 offset:1120
	ds_read_b128 v[134:137], v81 offset:3424
	ds_read_b128 v[138:141], v81 offset:1632
	ds_read_b128 v[142:145], v81 offset:3936
	s_waitcnt lgkmcnt(0)
	v_fmac_f32_e32 v86, v104, v130
	v_fma_f32 v86, -v9, v134, v86
	v_fmac_f32_e32 v86, v105, v131
	v_fma_f32 v86, -v14, v135, v86
	v_fmac_f32_e32 v86, v106, v132
	v_fma_f32 v86, -v16, v136, v86
	v_fmac_f32_e32 v86, v107, v133
	v_fma_f32 v86, -v17, v137, v86
	v_fmac_f32_e32 v87, v104, v138
	v_fma_f32 v87, -v9, v142, v87
	v_fmac_f32_e32 v87, v105, v139
	v_fma_f32 v87, -v14, v143, v87
	v_fmac_f32_e32 v87, v106, v140
	v_fma_f32 v87, -v16, v144, v87
	v_fmac_f32_e32 v87, v107, v141
	v_fma_f32 v87, -v17, v145, v87
	ds_read_b128 v[88:91], v80 offset:112
	ds_read_b128 v[92:95], v80 offset:4208
	ds_read2_b32 v[96:97], v82 offset1:16
	ds_read2_b32 v[98:99], v82 offset0:32 offset1:48
	ds_read2_b32 v[100:101], v83 offset1:16
	ds_read2_b32 v[102:103], v83 offset0:32 offset1:48
	ds_read_b128 v[130:133], v81 offset:112
	ds_read_b128 v[134:137], v81 offset:2416
	ds_read_b128 v[138:141], v81 offset:624
	ds_read_b128 v[142:145], v81 offset:2928
	s_waitcnt lgkmcnt(4)
; __device__ __forceinline__ void ssm_tables(const Params& p, int g, int part, LAS float* sm, int tid) {
;     ...
;     if (fa < 64 && fb > 32) {
;         for (int e = tid; e < 2048; e += 512) { const int l = e >> 8, pch = (e >> 4) & 15, q = e & 15; float s = 0.f;
;             for (int n = 0; n < 64; ++n) { const float cr = cre[pch * 64 + n], ci = cim[pch * 64 + n], ar = pwr[l * 64 + n], ai = pwi[l * 64 + n];
;                 const float zr = cr * ar - ci * ai, zi = cr * ai + ci * ar; s += zr * bbr[n * 16 + q] - zi * bbi[n * 16 + q]; }
;             kc[e] = s; }
;     }
	v_mul_f32_e32 v18, v92, v100
	v_mul_f32_e32 v9, v88, v100
	v_fma_f32 v104, v88, v96, -v18
	v_fmac_f32_e32 v9, v92, v96
	v_mul_f32_e32 v18, v93, v101
	v_mul_f32_e32 v14, v89, v101
	v_fma_f32 v105, v89, v97, -v18
	v_fmac_f32_e32 v14, v93, v97
	v_mul_f32_e32 v18, v94, v102
	v_mul_f32_e32 v16, v90, v102
	v_fma_f32 v106, v90, v98, -v18
	v_fmac_f32_e32 v16, v94, v98
	v_mul_f32_e32 v18, v95, v103
	v_mul_f32_e32 v17, v91, v103
	v_fma_f32 v107, v91, v99, -v18
	v_fmac_f32_e32 v17, v95, v99
	v_add_u32_e32 v82, 0x100, v82
	v_add_u32_e32 v83, 0x100, v83
	s_waitcnt lgkmcnt(0)
	v_fmac_f32_e32 v84, v104, v130
	v_fma_f32 v84, -v9, v134, v84
	v_fmac_f32_e32 v84, v105, v131
	v_fma_f32 v84, -v14, v135, v84
	v_fmac_f32_e32 v84, v106, v132
	v_fma_f32 v84, -v16, v136, v84
	v_fmac_f32_e32 v84, v107, v133
	v_fma_f32 v84, -v17, v137, v84
	v_fmac_f32_e32 v85, v104, v138
	v_fma_f32 v85, -v9, v142, v85
	v_fmac_f32_e32 v85, v105, v139
	v_fma_f32 v85, -v14, v143, v85
	v_fmac_f32_e32 v85, v106, v140
	v_fma_f32 v85, -v16, v144, v85
	v_fmac_f32_e32 v85, v107, v141
	v_fma_f32 v85, -v17, v145, v85
	ds_read_b128 v[130:133], v81 offset:1136
	ds_read_b128 v[134:137], v81 offset:3440
	ds_read_b128 v[138:141], v81 offset:1648
	ds_read_b128 v[142:145], v81 offset:3952
	s_waitcnt lgkmcnt(0)
	v_fmac_f32_e32 v86, v104, v130
	v_fma_f32 v86, -v9, v134, v86
	v_fmac_f32_e32 v86, v105, v131
	v_fma_f32 v86, -v14, v135, v86
	v_fmac_f32_e32 v86, v106, v132
	v_fma_f32 v86, -v16, v136, v86
	v_fmac_f32_e32 v86, v107, v133
	v_fma_f32 v86, -v17, v137, v86
	v_fmac_f32_e32 v87, v104, v138
	v_fma_f32 v87, -v9, v142, v87
	v_fmac_f32_e32 v87, v105, v139
	v_fma_f32 v87, -v14, v143, v87
	v_fmac_f32_e32 v87, v106, v140
	v_fma_f32 v87, -v16, v144, v87
	v_fmac_f32_e32 v87, v107, v141
	v_fma_f32 v87, -v17, v145, v87
	ds_read_b128 v[88:91], v80 offset:128
	ds_read_b128 v[92:95], v80 offset:4224
	ds_read2_b32 v[96:97], v82 offset1:16
	ds_read2_b32 v[98:99], v82 offset0:32 offset1:48
	ds_read2_b32 v[100:101], v83 offset1:16
	ds_read2_b32 v[102:103], v83 offset0:32 offset1:48
	ds_read_b128 v[130:133], v81 offset:128
	ds_read_b128 v[134:137], v81 offset:2432
	ds_read_b128 v[138:141], v81 offset:640
	ds_read_b128 v[142:145], v81 offset:2944
	s_waitcnt lgkmcnt(4)
	v_mul_f32_e32 v18, v92, v100
	v_mul_f32_e32 v9, v88, v100
	v_fma_f32 v104, v88, v96, -v18
	v_fmac_f32_e32 v9, v92, v96
	v_mul_f32_e32 v18, v93, v101
	v_mul_f32_e32 v14, v89, v101
	v_fma_f32 v105, v89, v97, -v18
	v_fmac_f32_e32 v14, v93, v97
	v_mul_f32_e32 v18, v94, v102
	v_mul_f32_e32 v16, v90, v102
	v_fma_f32 v106, v90, v98, -v18
	v_fmac_f32_e32 v16, v94, v98
	v_mul_f32_e32 v18, v95, v103
	v_mul_f32_e32 v17, v91, v103
	v_fma_f32 v107, v91, v99, -v18
	v_fmac_f32_e32 v17, v95, v99
	v_add_u32_e32 v82, 0x100, v82
	v_add_u32_e32 v83, 0x100, v83
	s_waitcnt lgkmcnt(0)
	v_fmac_f32_e32 v84, v104, v130
	v_fma_f32 v84, -v9, v134, v84
	v_fmac_f32_e32 v84, v105, v131
	v_fma_f32 v84, -v14, v135, v84
	v_fmac_f32_e32 v84, v106, v132
	v_fma_f32 v84, -v16, v136, v84
	v_fmac_f32_e32 v84, v107, v133
	v_fma_f32 v84, -v17, v137, v84
	v_fmac_f32_e32 v85, v104, v138
	v_fma_f32 v85, -v9, v142, v85
	v_fmac_f32_e32 v85, v105, v139
	v_fma_f32 v85, -v14, v143, v85
	v_fmac_f32_e32 v85, v106, v140
	v_fma_f32 v85, -v16, v144, v85
	v_fmac_f32_e32 v85, v107, v141
	v_fma_f32 v85, -v17, v145, v85
	ds_read_b128 v[130:133], v81 offset:1152
	ds_read_b128 v[134:137], v81 offset:3456
	ds_read_b128 v[138:141], v81 offset:1664
	ds_read_b128 v[142:145], v81 offset:3968
	s_waitcnt lgkmcnt(0)
	v_fmac_f32_e32 v86, v104, v130
	v_fma_f32 v86, -v9, v134, v86
	v_fmac_f32_e32 v86, v105, v131
	v_fma_f32 v86, -v14, v135, v86
	v_fmac_f32_e32 v86, v106, v132
	v_fma_f32 v86, -v16, v136, v86
	v_fmac_f32_e32 v86, v107, v133
	v_fma_f32 v86, -v17, v137, v86
	v_fmac_f32_e32 v87, v104, v138
	v_fma_f32 v87, -v9, v142, v87
	v_fmac_f32_e32 v87, v105, v139
	v_fma_f32 v87, -v14, v143, v87
	v_fmac_f32_e32 v87, v106, v140
	v_fma_f32 v87, -v16, v144, v87
	v_fmac_f32_e32 v87, v107, v141
	v_fma_f32 v87, -v17, v145, v87
	ds_read_b128 v[88:91], v80 offset:144
	ds_read_b128 v[92:95], v80 offset:4240
	ds_read2_b32 v[96:97], v82 offset1:16
	ds_read2_b32 v[98:99], v82 offset0:32 offset1:48
	ds_read2_b32 v[100:101], v83 offset1:16
	ds_read2_b32 v[102:103], v83 offset0:32 offset1:48
	ds_read_b128 v[130:133], v81 offset:144
	ds_read_b128 v[134:137], v81 offset:2448
	ds_read_b128 v[138:141], v81 offset:656
	ds_read_b128 v[142:145], v81 offset:2960
	s_waitcnt lgkmcnt(4)
	v_mul_f32_e32 v18, v92, v100
	v_mul_f32_e32 v9, v88, v100
	v_fma_f32 v104, v88, v96, -v18
	v_fmac_f32_e32 v9, v92, v96
	v_mul_f32_e32 v18, v93, v101
	v_mul_f32_e32 v14, v89, v101
	v_fma_f32 v105, v89, v97, -v18
	v_fmac_f32_e32 v14, v93, v97
	v_mul_f32_e32 v18, v94, v102
	v_mul_f32_e32 v16, v90, v102
	v_fma_f32 v106, v90, v98, -v18
	v_fmac_f32_e32 v16, v94, v98
	v_mul_f32_e32 v18, v95, v103
	v_mul_f32_e32 v17, v91, v103
	v_fma_f32 v107, v91, v99, -v18
	v_fmac_f32_e32 v17, v95, v99
	v_add_u32_e32 v82, 0x100, v82
	v_add_u32_e32 v83, 0x100, v83
	s_waitcnt lgkmcnt(0)
	v_fmac_f32_e32 v84, v104, v130
	v_fma_f32 v84, -v9, v134, v84
	v_fmac_f32_e32 v84, v105, v131
	v_fma_f32 v84, -v14, v135, v84
	v_fmac_f32_e32 v84, v106, v132
	v_fma_f32 v84, -v16, v136, v84
	v_fmac_f32_e32 v84, v107, v133
	v_fma_f32 v84, -v17, v137, v84
	v_fmac_f32_e32 v85, v104, v138
	v_fma_f32 v85, -v9, v142, v85
	v_fmac_f32_e32 v85, v105, v139
	v_fma_f32 v85, -v14, v143, v85
	v_fmac_f32_e32 v85, v106, v140
	v_fma_f32 v85, -v16, v144, v85
	v_fmac_f32_e32 v85, v107, v141
	v_fma_f32 v85, -v17, v145, v85
	ds_read_b128 v[130:133], v81 offset:1168
	ds_read_b128 v[134:137], v81 offset:3472
	ds_read_b128 v[138:141], v81 offset:1680
	ds_read_b128 v[142:145], v81 offset:3984
	s_waitcnt lgkmcnt(0)
; __device__ __forceinline__ void ssm_tables(const Params& p, int g, int part, LAS float* sm, int tid) {
;     ...
;     if (fa < 64 && fb > 32) {
;         for (int e = tid; e < 2048; e += 512) { const int l = e >> 8, pch = (e >> 4) & 15, q = e & 15; float s = 0.f;
;             for (int n = 0; n < 64; ++n) { const float cr = cre[pch * 64 + n], ci = cim[pch * 64 + n], ar = pwr[l * 64 + n], ai = pwi[l * 64 + n];
;                 const float zr = cr * ar - ci * ai, zi = cr * ai + ci * ar; s += zr * bbr[n * 16 + q] - zi * bbi[n * 16 + q]; }
;             kc[e] = s; }
;     }
	v_fmac_f32_e32 v86, v104, v130
	v_fma_f32 v86, -v9, v134, v86
	v_fmac_f32_e32 v86, v105, v131
	v_fma_f32 v86, -v14, v135, v86
	v_fmac_f32_e32 v86, v106, v132
	v_fma_f32 v86, -v16, v136, v86
	v_fmac_f32_e32 v86, v107, v133
	v_fma_f32 v86, -v17, v137, v86
	v_fmac_f32_e32 v87, v104, v138
	v_fma_f32 v87, -v9, v142, v87
	v_fmac_f32_e32 v87, v105, v139
	v_fma_f32 v87, -v14, v143, v87
	v_fmac_f32_e32 v87, v106, v140
	v_fma_f32 v87, -v16, v144, v87
	v_fmac_f32_e32 v87, v107, v141
	v_fma_f32 v87, -v17, v145, v87
	ds_read_b128 v[88:91], v80 offset:160
	ds_read_b128 v[92:95], v80 offset:4256
	ds_read2_b32 v[96:97], v82 offset1:16
	ds_read2_b32 v[98:99], v82 offset0:32 offset1:48
	ds_read2_b32 v[100:101], v83 offset1:16
	ds_read2_b32 v[102:103], v83 offset0:32 offset1:48
	ds_read_b128 v[130:133], v81 offset:160
	ds_read_b128 v[134:137], v81 offset:2464
	ds_read_b128 v[138:141], v81 offset:672
	ds_read_b128 v[142:145], v81 offset:2976
	s_waitcnt lgkmcnt(4)
	v_mul_f32_e32 v18, v92, v100
	v_mul_f32_e32 v9, v88, v100
	v_fma_f32 v104, v88, v96, -v18
	v_fmac_f32_e32 v9, v92, v96
	v_mul_f32_e32 v18, v93, v101
	v_mul_f32_e32 v14, v89, v101
	v_fma_f32 v105, v89, v97, -v18
	v_fmac_f32_e32 v14, v93, v97
	v_mul_f32_e32 v18, v94, v102
	v_mul_f32_e32 v16, v90, v102
	v_fma_f32 v106, v90, v98, -v18
	v_fmac_f32_e32 v16, v94, v98
	v_mul_f32_e32 v18, v95, v103
	v_mul_f32_e32 v17, v91, v103
	v_fma_f32 v107, v91, v99, -v18
	v_fmac_f32_e32 v17, v95, v99
	v_add_u32_e32 v82, 0x100, v82
	v_add_u32_e32 v83, 0x100, v83
	s_waitcnt lgkmcnt(0)
	v_fmac_f32_e32 v84, v104, v130
	v_fma_f32 v84, -v9, v134, v84
	v_fmac_f32_e32 v84, v105, v131
	v_fma_f32 v84, -v14, v135, v84
	v_fmac_f32_e32 v84, v106, v132
	v_fma_f32 v84, -v16, v136, v84
	v_fmac_f32_e32 v84, v107, v133
	v_fma_f32 v84, -v17, v137, v84
	v_fmac_f32_e32 v85, v104, v138
	v_fma_f32 v85, -v9, v142, v85
	v_fmac_f32_e32 v85, v105, v139
	v_fma_f32 v85, -v14, v143, v85
	v_fmac_f32_e32 v85, v106, v140
	v_fma_f32 v85, -v16, v144, v85
	v_fmac_f32_e32 v85, v107, v141
	v_fma_f32 v85, -v17, v145, v85
	ds_read_b128 v[130:133], v81 offset:1184
	ds_read_b128 v[134:137], v81 offset:3488
	ds_read_b128 v[138:141], v81 offset:1696
	ds_read_b128 v[142:145], v81 offset:4000
	s_waitcnt lgkmcnt(0)
	v_fmac_f32_e32 v86, v104, v130
	v_fma_f32 v86, -v9, v134, v86
	v_fmac_f32_e32 v86, v105, v131
	v_fma_f32 v86, -v14, v135, v86
	v_fmac_f32_e32 v86, v106, v132
	v_fma_f32 v86, -v16, v136, v86
	v_fmac_f32_e32 v86, v107, v133
	v_fma_f32 v86, -v17, v137, v86
	v_fmac_f32_e32 v87, v104, v138
	v_fma_f32 v87, -v9, v142, v87
	v_fmac_f32_e32 v87, v105, v139
	v_fma_f32 v87, -v14, v143, v87
	v_fmac_f32_e32 v87, v106, v140
	v_fma_f32 v87, -v16, v144, v87
	v_fmac_f32_e32 v87, v107, v141
	v_fma_f32 v87, -v17, v145, v87
	ds_read_b128 v[88:91], v80 offset:176
	ds_read_b128 v[92:95], v80 offset:4272
	ds_read2_b32 v[96:97], v82 offset1:16
	ds_read2_b32 v[98:99], v82 offset0:32 offset1:48
	ds_read2_b32 v[100:101], v83 offset1:16
	ds_read2_b32 v[102:103], v83 offset0:32 offset1:48
	ds_read_b128 v[130:133], v81 offset:176
	ds_read_b128 v[134:137], v81 offset:2480
	ds_read_b128 v[138:141], v81 offset:688
	ds_read_b128 v[142:145], v81 offset:2992
	s_waitcnt lgkmcnt(4)
	v_mul_f32_e32 v18, v92, v100
	v_mul_f32_e32 v9, v88, v100
	v_fma_f32 v104, v88, v96, -v18
	v_fmac_f32_e32 v9, v92, v96
	v_mul_f32_e32 v18, v93, v101
	v_mul_f32_e32 v14, v89, v101
	v_fma_f32 v105, v89, v97, -v18
	v_fmac_f32_e32 v14, v93, v97
	v_mul_f32_e32 v18, v94, v102
	v_mul_f32_e32 v16, v90, v102
	v_fma_f32 v106, v90, v98, -v18
	v_fmac_f32_e32 v16, v94, v98
	v_mul_f32_e32 v18, v95, v103
	v_mul_f32_e32 v17, v91, v103
	v_fma_f32 v107, v91, v99, -v18
	v_fmac_f32_e32 v17, v95, v99
	v_add_u32_e32 v82, 0x100, v82
	v_add_u32_e32 v83, 0x100, v83
	s_waitcnt lgkmcnt(0)
	v_fmac_f32_e32 v84, v104, v130
	v_fma_f32 v84, -v9, v134, v84
	v_fmac_f32_e32 v84, v105, v131
	v_fma_f32 v84, -v14, v135, v84
	v_fmac_f32_e32 v84, v106, v132
	v_fma_f32 v84, -v16, v136, v84
	v_fmac_f32_e32 v84, v107, v133
	v_fma_f32 v84, -v17, v137, v84
	v_fmac_f32_e32 v85, v104, v138
	v_fma_f32 v85, -v9, v142, v85
	v_fmac_f32_e32 v85, v105, v139
	v_fma_f32 v85, -v14, v143, v85
	v_fmac_f32_e32 v85, v106, v140
	v_fma_f32 v85, -v16, v144, v85
	v_fmac_f32_e32 v85, v107, v141
	v_fma_f32 v85, -v17, v145, v85
	ds_read_b128 v[130:133], v81 offset:1200
	ds_read_b128 v[134:137], v81 offset:3504
	ds_read_b128 v[138:141], v81 offset:1712
	ds_read_b128 v[142:145], v81 offset:4016
	s_waitcnt lgkmcnt(0)
	v_fmac_f32_e32 v86, v104, v130
	v_fma_f32 v86, -v9, v134, v86
	v_fmac_f32_e32 v86, v105, v131
	v_fma_f32 v86, -v14, v135, v86
	v_fmac_f32_e32 v86, v106, v132
	v_fma_f32 v86, -v16, v136, v86
	v_fmac_f32_e32 v86, v107, v133
	v_fma_f32 v86, -v17, v137, v86
	v_fmac_f32_e32 v87, v104, v138
	v_fma_f32 v87, -v9, v142, v87
	v_fmac_f32_e32 v87, v105, v139
	v_fma_f32 v87, -v14, v143, v87
	v_fmac_f32_e32 v87, v106, v140
	v_fma_f32 v87, -v16, v144, v87
	v_fmac_f32_e32 v87, v107, v141
	v_fma_f32 v87, -v17, v145, v87
	ds_read_b128 v[88:91], v80 offset:192
	ds_read_b128 v[92:95], v80 offset:4288
	ds_read2_b32 v[96:97], v82 offset1:16
	ds_read2_b32 v[98:99], v82 offset0:32 offset1:48
	ds_read2_b32 v[100:101], v83 offset1:16
	ds_read2_b32 v[102:103], v83 offset0:32 offset1:48
	ds_read_b128 v[130:133], v81 offset:192
	ds_read_b128 v[134:137], v81 offset:2496
	ds_read_b128 v[138:141], v81 offset:704
	ds_read_b128 v[142:145], v81 offset:3008
	s_waitcnt lgkmcnt(4)
; __device__ __forceinline__ void ssm_tables(const Params& p, int g, int part, LAS float* sm, int tid) {
;     ...
;     if (fa < 64 && fb > 32) {
;         for (int e = tid; e < 2048; e += 512) { const int l = e >> 8, pch = (e >> 4) & 15, q = e & 15; float s = 0.f;
;             for (int n = 0; n < 64; ++n) { const float cr = cre[pch * 64 + n], ci = cim[pch * 64 + n], ar = pwr[l * 64 + n], ai = pwi[l * 64 + n];
;                 const float zr = cr * ar - ci * ai, zi = cr * ai + ci * ar; s += zr * bbr[n * 16 + q] - zi * bbi[n * 16 + q]; }
;             kc[e] = s; }
;     }
	v_mul_f32_e32 v18, v92, v100
	v_mul_f32_e32 v9, v88, v100
	v_fma_f32 v104, v88, v96, -v18
	v_fmac_f32_e32 v9, v92, v96
	v_mul_f32_e32 v18, v93, v101
	v_mul_f32_e32 v14, v89, v101
	v_fma_f32 v105, v89, v97, -v18
	v_fmac_f32_e32 v14, v93, v97
	v_mul_f32_e32 v18, v94, v102
	v_mul_f32_e32 v16, v90, v102
	v_fma_f32 v106, v90, v98, -v18
	v_fmac_f32_e32 v16, v94, v98
	v_mul_f32_e32 v18, v95, v103
	v_mul_f32_e32 v17, v91, v103
	v_fma_f32 v107, v91, v99, -v18
	v_fmac_f32_e32 v17, v95, v99
	v_add_u32_e32 v82, 0x100, v82
	v_add_u32_e32 v83, 0x100, v83
	s_waitcnt lgkmcnt(0)
	v_fmac_f32_e32 v84, v104, v130
	v_fma_f32 v84, -v9, v134, v84
	v_fmac_f32_e32 v84, v105, v131
	v_fma_f32 v84, -v14, v135, v84
	v_fmac_f32_e32 v84, v106, v132
	v_fma_f32 v84, -v16, v136, v84
	v_fmac_f32_e32 v84, v107, v133
	v_fma_f32 v84, -v17, v137, v84
	v_fmac_f32_e32 v85, v104, v138
	v_fma_f32 v85, -v9, v142, v85
	v_fmac_f32_e32 v85, v105, v139
	v_fma_f32 v85, -v14, v143, v85
	v_fmac_f32_e32 v85, v106, v140
	v_fma_f32 v85, -v16, v144, v85
	v_fmac_f32_e32 v85, v107, v141
	v_fma_f32 v85, -v17, v145, v85
	ds_read_b128 v[130:133], v81 offset:1216
	ds_read_b128 v[134:137], v81 offset:3520
	ds_read_b128 v[138:141], v81 offset:1728
	ds_read_b128 v[142:145], v81 offset:4032
	s_waitcnt lgkmcnt(0)
	v_fmac_f32_e32 v86, v104, v130
	v_fma_f32 v86, -v9, v134, v86
	v_fmac_f32_e32 v86, v105, v131
	v_fma_f32 v86, -v14, v135, v86
	v_fmac_f32_e32 v86, v106, v132
	v_fma_f32 v86, -v16, v136, v86
	v_fmac_f32_e32 v86, v107, v133
	v_fma_f32 v86, -v17, v137, v86
	v_fmac_f32_e32 v87, v104, v138
	v_fma_f32 v87, -v9, v142, v87
	v_fmac_f32_e32 v87, v105, v139
	v_fma_f32 v87, -v14, v143, v87
	v_fmac_f32_e32 v87, v106, v140
	v_fma_f32 v87, -v16, v144, v87
	v_fmac_f32_e32 v87, v107, v141
	v_fma_f32 v87, -v17, v145, v87
	ds_read_b128 v[88:91], v80 offset:208
	ds_read_b128 v[92:95], v80 offset:4304
	ds_read2_b32 v[96:97], v82 offset1:16
	ds_read2_b32 v[98:99], v82 offset0:32 offset1:48
	ds_read2_b32 v[100:101], v83 offset1:16
	ds_read2_b32 v[102:103], v83 offset0:32 offset1:48
	ds_read_b128 v[130:133], v81 offset:208
	ds_read_b128 v[134:137], v81 offset:2512
	ds_read_b128 v[138:141], v81 offset:720
	ds_read_b128 v[142:145], v81 offset:3024
	s_waitcnt lgkmcnt(4)
	v_mul_f32_e32 v18, v92, v100
	v_mul_f32_e32 v9, v88, v100
	v_fma_f32 v104, v88, v96, -v18
	v_fmac_f32_e32 v9, v92, v96
	v_mul_f32_e32 v18, v93, v101
	v_mul_f32_e32 v14, v89, v101
	v_fma_f32 v105, v89, v97, -v18
	v_fmac_f32_e32 v14, v93, v97
	v_mul_f32_e32 v18, v94, v102
	v_mul_f32_e32 v16, v90, v102
	v_fma_f32 v106, v90, v98, -v18
	v_fmac_f32_e32 v16, v94, v98
	v_mul_f32_e32 v18, v95, v103
	v_mul_f32_e32 v17, v91, v103
	v_fma_f32 v107, v91, v99, -v18
	v_fmac_f32_e32 v17, v95, v99
	v_add_u32_e32 v82, 0x100, v82
	v_add_u32_e32 v83, 0x100, v83
	s_waitcnt lgkmcnt(0)
	v_fmac_f32_e32 v84, v104, v130
	v_fma_f32 v84, -v9, v134, v84
	v_fmac_f32_e32 v84, v105, v131
	v_fma_f32 v84, -v14, v135, v84
	v_fmac_f32_e32 v84, v106, v132
	v_fma_f32 v84, -v16, v136, v84
	v_fmac_f32_e32 v84, v107, v133
	v_fma_f32 v84, -v17, v137, v84
	v_fmac_f32_e32 v85, v104, v138
	v_fma_f32 v85, -v9, v142, v85
	v_fmac_f32_e32 v85, v105, v139
	v_fma_f32 v85, -v14, v143, v85
	v_fmac_f32_e32 v85, v106, v140
	v_fma_f32 v85, -v16, v144, v85
	v_fmac_f32_e32 v85, v107, v141
	v_fma_f32 v85, -v17, v145, v85
	ds_read_b128 v[130:133], v81 offset:1232
	ds_read_b128 v[134:137], v81 offset:3536
	ds_read_b128 v[138:141], v81 offset:1744
	ds_read_b128 v[142:145], v81 offset:4048
	s_waitcnt lgkmcnt(0)
	v_fmac_f32_e32 v86, v104, v130
	v_fma_f32 v86, -v9, v134, v86
	v_fmac_f32_e32 v86, v105, v131
	v_fma_f32 v86, -v14, v135, v86
	v_fmac_f32_e32 v86, v106, v132
	v_fma_f32 v86, -v16, v136, v86
	v_fmac_f32_e32 v86, v107, v133
	v_fma_f32 v86, -v17, v137, v86
	v_fmac_f32_e32 v87, v104, v138
	v_fma_f32 v87, -v9, v142, v87
	v_fmac_f32_e32 v87, v105, v139
	v_fma_f32 v87, -v14, v143, v87
	v_fmac_f32_e32 v87, v106, v140
	v_fma_f32 v87, -v16, v144, v87
	v_fmac_f32_e32 v87, v107, v141
	v_fma_f32 v87, -v17, v145, v87
	ds_read_b128 v[88:91], v80 offset:224
	ds_read_b128 v[92:95], v80 offset:4320
	ds_read2_b32 v[96:97], v82 offset1:16
	ds_read2_b32 v[98:99], v82 offset0:32 offset1:48
	ds_read2_b32 v[100:101], v83 offset1:16
	ds_read2_b32 v[102:103], v83 offset0:32 offset1:48
	ds_read_b128 v[130:133], v81 offset:224
	ds_read_b128 v[134:137], v81 offset:2528
	ds_read_b128 v[138:141], v81 offset:736
	ds_read_b128 v[142:145], v81 offset:3040
	s_waitcnt lgkmcnt(4)
; __device__ __forceinline__ void ssm_tables(const Params& p, int g, int part, LAS float* sm, int tid) {
;     ...
;     if (fa < 64 && fb > 32) {
;         for (int e = tid; e < 2048; e += 512) { const int l = e >> 8, pch = (e >> 4) & 15, q = e & 15; float s = 0.f;
;             for (int n = 0; n < 64; ++n) { const float cr = cre[pch * 64 + n], ci = cim[pch * 64 + n], ar = pwr[l * 64 + n], ai = pwi[l * 64 + n];
;                 const float zr = cr * ar - ci * ai, zi = cr * ai + ci * ar; s += zr * bbr[n * 16 + q] - zi * bbi[n * 16 + q]; }
;             kc[e] = s; }
;     }
	v_mul_f32_e32 v18, v92, v100
	v_mul_f32_e32 v9, v88, v100
	v_fma_f32 v104, v88, v96, -v18
	v_fmac_f32_e32 v9, v92, v96
	v_mul_f32_e32 v18, v93, v101
	v_mul_f32_e32 v14, v89, v101
	v_fma_f32 v105, v89, v97, -v18
	v_fmac_f32_e32 v14, v93, v97
	v_mul_f32_e32 v18, v94, v102
	v_mul_f32_e32 v16, v90, v102
	v_fma_f32 v106, v90, v98, -v18
	v_fmac_f32_e32 v16, v94, v98
	v_mul_f32_e32 v18, v95, v103
	v_mul_f32_e32 v17, v91, v103
	v_fma_f32 v107, v91, v99, -v18
	v_fmac_f32_e32 v17, v95, v99
	v_add_u32_e32 v82, 0x100, v82
	v_add_u32_e32 v83, 0x100, v83
	s_waitcnt lgkmcnt(0)
	v_fmac_f32_e32 v84, v104, v130
	v_fma_f32 v84, -v9, v134, v84
	v_fmac_f32_e32 v84, v105, v131
	v_fma_f32 v84, -v14, v135, v84
	v_fmac_f32_e32 v84, v106, v132
	v_fma_f32 v84, -v16, v136, v84
	v_fmac_f32_e32 v84, v107, v133
	v_fma_f32 v84, -v17, v137, v84
	v_fmac_f32_e32 v85, v104, v138
	v_fma_f32 v85, -v9, v142, v85
	v_fmac_f32_e32 v85, v105, v139
	v_fma_f32 v85, -v14, v143, v85
	v_fmac_f32_e32 v85, v106, v140
	v_fma_f32 v85, -v16, v144, v85
	v_fmac_f32_e32 v85, v107, v141
	v_fma_f32 v85, -v17, v145, v85
	ds_read_b128 v[130:133], v81 offset:1248
	ds_read_b128 v[134:137], v81 offset:3552
	ds_read_b128 v[138:141], v81 offset:1760
	ds_read_b128 v[142:145], v81 offset:4064
	s_waitcnt lgkmcnt(0)
	v_fmac_f32_e32 v86, v104, v130
	v_fma_f32 v86, -v9, v134, v86
	v_fmac_f32_e32 v86, v105, v131
	v_fma_f32 v86, -v14, v135, v86
	v_fmac_f32_e32 v86, v106, v132
	v_fma_f32 v86, -v16, v136, v86
	v_fmac_f32_e32 v86, v107, v133
	v_fma_f32 v86, -v17, v137, v86
	v_fmac_f32_e32 v87, v104, v138
	v_fma_f32 v87, -v9, v142, v87
	v_fmac_f32_e32 v87, v105, v139
	v_fma_f32 v87, -v14, v143, v87
	v_fmac_f32_e32 v87, v106, v140
	v_fma_f32 v87, -v16, v144, v87
	v_fmac_f32_e32 v87, v107, v141
	v_fma_f32 v87, -v17, v145, v87
	ds_read_b128 v[88:91], v80 offset:240
	ds_read_b128 v[92:95], v80 offset:4336
	ds_read2_b32 v[96:97], v82 offset1:16
	ds_read2_b32 v[98:99], v82 offset0:32 offset1:48
	ds_read2_b32 v[100:101], v83 offset1:16
	ds_read2_b32 v[102:103], v83 offset0:32 offset1:48
	ds_read_b128 v[130:133], v81 offset:240
	ds_read_b128 v[134:137], v81 offset:2544
	ds_read_b128 v[138:141], v81 offset:752
	ds_read_b128 v[142:145], v81 offset:3056
	s_waitcnt lgkmcnt(4)
	v_mul_f32_e32 v18, v92, v100
	v_mul_f32_e32 v9, v88, v100
	v_fma_f32 v104, v88, v96, -v18
	v_fmac_f32_e32 v9, v92, v96
	v_mul_f32_e32 v18, v93, v101
	v_mul_f32_e32 v14, v89, v101
	v_fma_f32 v105, v89, v97, -v18
	v_fmac_f32_e32 v14, v93, v97
	v_mul_f32_e32 v18, v94, v102
	v_mul_f32_e32 v16, v90, v102
	v_fma_f32 v106, v90, v98, -v18
	v_fmac_f32_e32 v16, v94, v98
	v_mul_f32_e32 v18, v95, v103
	v_mul_f32_e32 v17, v91, v103
	v_fma_f32 v107, v91, v99, -v18
	v_fmac_f32_e32 v17, v95, v99
	v_add_u32_e32 v82, 0x100, v82
	v_add_u32_e32 v83, 0x100, v83
	s_waitcnt lgkmcnt(0)
	v_fmac_f32_e32 v84, v104, v130
	v_fma_f32 v84, -v9, v134, v84
	v_fmac_f32_e32 v84, v105, v131
	v_fma_f32 v84, -v14, v135, v84
	v_fmac_f32_e32 v84, v106, v132
	v_fma_f32 v84, -v16, v136, v84
	v_fmac_f32_e32 v84, v107, v133
	v_fma_f32 v84, -v17, v137, v84
	v_fmac_f32_e32 v85, v104, v138
	v_fma_f32 v85, -v9, v142, v85
	v_fmac_f32_e32 v85, v105, v139
	v_fma_f32 v85, -v14, v143, v85
	v_fmac_f32_e32 v85, v106, v140
	v_fma_f32 v85, -v16, v144, v85
	v_fmac_f32_e32 v85, v107, v141
	v_fma_f32 v85, -v17, v145, v85
	ds_read_b128 v[130:133], v81 offset:1264
	ds_read_b128 v[134:137], v81 offset:3568
	ds_read_b128 v[138:141], v81 offset:1776
	ds_read_b128 v[142:145], v81 offset:4080
	s_waitcnt lgkmcnt(0)
	v_fmac_f32_e32 v86, v104, v130
	v_fma_f32 v86, -v9, v134, v86
	v_fmac_f32_e32 v86, v105, v131
	v_fma_f32 v86, -v14, v135, v86
	v_fmac_f32_e32 v86, v106, v132
	v_fma_f32 v86, -v16, v136, v86
	v_fmac_f32_e32 v86, v107, v133
	v_fma_f32 v86, -v17, v137, v86
	v_fmac_f32_e32 v87, v104, v138
	v_fma_f32 v87, -v9, v142, v87
	v_fmac_f32_e32 v87, v105, v139
	v_fma_f32 v87, -v14, v143, v87
	v_fmac_f32_e32 v87, v106, v140
	v_fma_f32 v87, -v16, v144, v87
	v_fmac_f32_e32 v87, v107, v141
	v_fma_f32 v87, -v17, v145, v87
	v_lshlrev_b32_e32 v80, 2, v34
	ds_write_b32 v80, v84 offset:21504
	ds_write_b32 v80, v85 offset:23552
	ds_write_b32 v80, v86 offset:25600
	ds_write_b32 v80, v87 offset:27648
	s_waitcnt lgkmcnt(0)
